# dilated attention: K subtile loaded row-contiguously (4 rows x 256 B per instruction, V addresses +768) and transposed to the MFMA A-fragment layout through per-wave LDS; was a 32-row x 32-B gather pe
# speedup vs baseline: 1.0189x; 1.0108x over previous
.LBB0_506:
	s_andn2_b64 vcc, exec, s[4:5]
	s_cbranch_vccnz .LBB0_535
	v_mov_b32_e32 v0, v252
	s_andn2_b64 vcc, exec, s[12:13]
	s_cbranch_vccnz .LBB0_523
	v_readlane_b32 s4, v255, 2
	s_lshl_b32 s4, s4, 14
	v_lshl_add_u32 v2, v0, 3, s4
	v_add_u32_e32 v2, 0x3300, v2
	ds_write_b32 v2, v197
	ds_write_b32 v2, v198 offset:4
	s_waitcnt lgkmcnt(0)
	v_lshrrev_b32_e32 v197, 4, v0
	v_and_b32_e32 v3, 15, v0
	v_mul_u32_u24_e32 v197, 0x110, v197
	v_lshl_add_u32 v197, v3, 4, v197
	v_add_u32_e32 v197, s4, v197
	v_and_b32_e32 v198, 31, v0
	v_lshrrev_b32_e32 v3, 4, v198
	v_mul_u32_u24_e32 v3, 0x1100, v3
	v_mul_u32_u24_e32 v198, 0x110, v198
	v_add_u32_e32 v198, v198, v3
	v_lshrrev_b32_e32 v3, 5, v0
	v_lshl_add_u32 v198, v3, 4, v198
	v_add_u32_e32 v198, s4, v198
	v_lshlrev_b32_e32 v3, 4, v0
	v_ashrrev_i32_e32 v204, 4, v0
	v_lshlrev_b32_e32 v2, 3, v0
	v_and_b32_e32 v3, 0xc0, v3
	v_lshlrev_b32_e32 v5, 1, v0
	v_add_u32_e32 v207, 4, v204
	v_and_or_b32 v3, v2, 24, v3
	v_and_b32_e32 v5, 32, v5
	v_and_b32_e32 v2, 0x100, v2
	v_and_b32_e32 v10, 0xfffff0, v207
	v_lshlrev_b32_e32 v11, 1, v207
	v_or3_b32 v5, v3, v5, v2
	v_and_or_b32 v10, v11, 8, v10
	v_add_u32_e32 v203, s71, v5
	v_bfe_u32 v5, v0, 2, 2
	v_and_b32_e32 v7, 3, v204
	v_lshrrev_b32_e32 v11, 1, v207
	v_lshrrev_b32_e32 v10, 1, v10
	v_or_b32_e32 v10, v10, v5
	v_and_or_b32 v11, v11, 4, v7
	v_lshlrev_b32_e32 v10, 9, v10
	v_lshlrev_b32_e32 v11, 6, v11
	v_add_u32_e32 v208, 8, v204
	v_add3_u32 v10, s71, v11, v10
	v_and_b32_e32 v11, 0xfffff0, v208
	v_lshlrev_b32_e32 v12, 1, v208
	v_and_or_b32 v11, v12, 8, v11
	v_lshrrev_b32_e32 v12, 1, v208
	v_lshrrev_b32_e32 v11, 1, v11
	v_or_b32_e32 v11, v11, v5
	v_and_or_b32 v12, v12, 4, v7
	v_lshlrev_b32_e32 v11, 9, v11
	v_lshlrev_b32_e32 v12, 6, v12
	v_add_u32_e32 v209, 12, v204
	v_add3_u32 v11, s71, v12, v11
	v_and_b32_e32 v12, 0xfffff0, v209
	v_lshlrev_b32_e32 v13, 1, v209
	v_and_or_b32 v12, v13, 8, v12
	v_lshrrev_b32_e32 v13, 1, v209
	v_lshrrev_b32_e32 v12, 1, v12
	v_or_b32_e32 v12, v12, v5
	v_and_or_b32 v13, v13, 4, v7
	s_lshl_b32 s4, s84, 2
	v_lshlrev_b32_e32 v12, 9, v12
	v_lshlrev_b32_e32 v13, 6, v13
	v_add_u32_e32 v210, 16, v204
	v_and_b32_e32 v181, 31, v0
	v_ashrrev_i32_e32 v4, 5, v0
	s_or_b32 s33, s4, 1
	v_and_b32_e32 v6, 15, v0
	v_cmp_gt_u32_e64 s[6:7], 32, v0
	v_cmp_lt_u32_e64 s[4:5], 31, v0
	v_and_b32_e32 v0, 0xfffff0, v204
	v_lshlrev_b32_e32 v9, 1, v204
	v_add3_u32 v12, s71, v13, v12
	v_and_b32_e32 v13, 0xfffff0, v210
	v_lshlrev_b32_e32 v14, 1, v210
	v_and_or_b32 v0, v9, 8, v0
	v_lshrrev_b32_e32 v9, 1, v204
	v_and_or_b32 v13, v14, 8, v13
	v_lshrrev_b32_e32 v0, 1, v0
	v_and_or_b32 v9, v9, 4, v7
	v_lshrrev_b32_e32 v13, 1, v13
	v_or_b32_e32 v0, v0, v5
	v_lshl_add_u32 v9, v9, 6, s71
	v_or_b32_e32 v13, v13, v5
	v_add_u32_e32 v211, 20, v204
	v_lshl_add_u32 v0, v0, 9, v9
	v_lshl_add_u32 v9, v13, 9, v9
	v_and_b32_e32 v13, 0xfffff0, v211
	v_lshlrev_b32_e32 v14, 1, v211
	v_and_or_b32 v13, v14, 8, v13
	v_lshrrev_b32_e32 v14, 1, v211
	v_lshrrev_b32_e32 v13, 1, v13
	v_or_b32_e32 v13, v13, v5
	v_and_or_b32 v14, v14, 4, v7
	v_lshlrev_b32_e32 v13, 9, v13
	v_lshlrev_b32_e32 v14, 6, v14
	v_add_u32_e32 v212, 24, v204
	v_add3_u32 v13, s71, v14, v13
	v_and_b32_e32 v14, 0xfffff0, v212
	v_lshlrev_b32_e32 v15, 1, v212
	v_and_or_b32 v14, v15, 8, v14
	v_lshrrev_b32_e32 v15, 1, v212
	v_lshrrev_b32_e32 v14, 1, v14
	v_or_b32_e32 v14, v14, v5
	v_and_or_b32 v15, v15, 4, v7
	v_lshlrev_b32_e32 v14, 9, v14
	v_lshlrev_b32_e32 v15, 6, v15
	v_add_u32_e32 v213, 28, v204
	v_add3_u32 v14, s71, v15, v14
	v_and_b32_e32 v15, 0xfffff0, v213
	v_lshlrev_b32_e32 v16, 1, v213
	v_and_or_b32 v15, v16, 8, v15
	v_lshrrev_b32_e32 v16, 1, v213
	v_lshrrev_b32_e32 v15, 1, v15
	v_or_b32_e32 v5, v15, v5
	v_and_or_b32 v7, v16, 4, v7
	v_lshlrev_b32_e32 v205, 2, v4
	v_lshlrev_b32_e32 v5, 9, v5
	v_lshlrev_b32_e32 v7, 6, v7
	s_movk_i32 s8, 0x440
	v_lshlrev_b32_e32 v2, 3, v4
	v_add3_u32 v5, s71, v7, v5
	v_lshl_add_u32 v214, v4, 4, s71
	v_or_b32_e32 v7, 1, v205
	v_mul_lo_u32 v4, v4, s8
	s_movk_i32 s8, 0x110
	v_mul_lo_u32 v7, v7, s8
	v_lshlrev_b32_e32 v180, 3, v6
	v_lshlrev_b32_e32 v6, 4, v6
	v_add_u32_e32 v216, s71, v7
	v_ashrrev_i32_e32 v3, 31, v2
	v_and_b32_e32 v8, 48, v6
	v_lshlrev_b32_e32 v215, 1, v181
	v_add_u32_e32 v4, s71, v4
	v_add_u32_e32 v7, 0x110, v216
	v_add_u32_e32 v15, 0x220, v216
	v_add_u32_e32 v16, 0x770, v216
	v_add_u32_e32 v17, 0x880, v216
	v_add_u32_e32 v18, 0x990, v216
	v_add_u32_e32 v19, 0xaa0, v216
	v_add_u32_e32 v20, 0xff0, v216
	v_add_u32_e32 v21, 0x1100, v216
	v_add_u32_e32 v22, 0x1210, v216
	v_add_u32_e32 v23, 0x1320, v216
	v_add_u32_e32 v24, 0x1870, v216
	v_add_u32_e32 v25, 0x1980, v216
	v_add_u32_e32 v26, 0x1a90, v216
	v_add_u32_e32 v27, 0x1ba0, v216
	v_add_u32_e32 v6, s71, v6
	v_mul_lo_u32 v28, v204, s8
	v_lshl_add_u32 v206, v181, 2, s71
	v_sub_u32_e32 v217, 0, v205
	v_lshlrev_b64 v[182:183], 1, v[2:3]
	v_add_u32_e32 v218, v0, v8
	v_add_u32_e32 v219, v10, v8
	v_add_u32_e32 v220, v11, v8
	v_add_u32_e32 v221, v12, v8
	v_add_u32_e32 v222, v9, v8
	v_add_u32_e32 v223, v13, v8
	v_add_u32_e32 v224, v14, v8
	v_add_u32_e32 v225, v5, v8
	v_add_u32_e32 v226, v4, v215
	v_add_u32_e32 v227, v7, v215
	v_add_u32_e32 v228, v15, v215
	v_add_u32_e32 v229, v16, v215
	v_add_u32_e32 v230, v17, v215
	v_add_u32_e32 v231, v18, v215
	v_add_u32_e32 v232, v19, v215
	v_add_u32_e32 v233, v20, v215
	v_add_u32_e32 v234, v21, v215
	v_add_u32_e32 v235, v22, v215
	v_add_u32_e32 v236, v23, v215
	v_add_u32_e32 v237, v24, v215
	v_add_u32_e32 v238, v25, v215
	v_add_u32_e32 v239, v26, v215
	v_add_u32_e32 v240, v27, v215
	v_add_u32_e32 v241, v6, v28
	s_mov_b32 s54, s66
	s_branch .LBB0_510

.LBB0_510:
	s_ashr_i32 s8, s54, 9
	s_mul_hi_i32 s10, s8, 0x55555556
	s_lshr_b32 s11, s10, 31
	s_add_i32 s10, s10, s11
	s_mul_i32 s11, s10, 3
	s_sub_i32 s50, s8, s11
	s_mul_hi_i32 s8, s8, 0x2aaaaaab
	s_and_b32 s57, s10, 3
	s_lshr_b32 s10, s8, 31
	s_ashr_i32 s8, s8, 1
	s_lshl_b32 s55, s50, 1
	s_add_i32 s8, s8, s10
	s_lshr_b32 s10, 0x200, s55
	s_and_b32 s9, s54, 0x1ff
	s_add_i32 s10, s10, -1
	s_sub_i32 s11, 9, s55
	s_and_b32 s18, s10, s9
	s_lshr_b32 s72, s9, s11
	s_lshl_b32 s56, s18, 5
	s_ashr_i32 s9, s8, 31
	s_lshl_b64 s[52:53], s[8:9], 14
	v_or_b32_e32 v0, s56, v181
	v_lshlrev_b64 v[186:187], s55, v[0:1]
	s_or_b32 s10, s52, s72
	s_mov_b32 s11, s53
	v_lshl_add_u64 v[2:3], v[186:187], 0, s[10:11]
	v_mov_b64_e32 v[4:5], s[26:27]
	v_mad_u64_u32 v[4:5], s[16:17], v2, s83, v[4:5]
	v_mov_b32_e32 v0, v5
	v_mad_u64_u32 v[2:3], s[16:17], v3, s83, v[0:1]
	s_add_i32 s16, s33, s57
	s_nop 0
	v_cvt_f32_u32_e32 v8, s16
	s_mul_i32 s8, s57, 0x480
	s_lshl_b32 s9, s50, 7
	s_add_i32 s8, s8, s9
	s_ashr_i32 s9, s8, 31
	v_mul_f32_e32 v0, -0.5, v8
	s_mov_b32 s16, 0xc2fc0000
	s_lshl_b64 s[8:9], s[8:9], 1
	s_lshl_b32 s19, 1, s55
	v_cmp_gt_f32_e32 vcc, s16, v0
	v_mov_b32_e32 v5, v2
	s_and_b64 s[16:17], vcc, exec
	v_lshl_add_u64 v[2:3], v[4:5], 0, s[8:9]
	s_cselect_b32 s16, 0xffffffc0, 0
	s_add_u32 s8, s26, s8
	s_addc_u32 s9, s27, s9
	s_sub_i32 s17, 0x80, s56
	s_ashr_i32 s17, s17, 5
	s_cmp_lt_u32 s18, 4
	s_cselect_b32 s17, s17, 0
	s_lshl_b32 s18, s17, 5
	s_add_i32 s30, s56, s18
	s_add_i32 s51, s30, 0xffffff80
	v_add_u32_e32 v10, s51, v204
	v_max_i32_e32 v0, 0xffffffe4, v10
	v_lshl_add_u64 v[2:3], v[2:3], 0, v[182:183]
	v_add_u32_e32 v0, 28, v0
	global_load_dwordx4 v[82:85], v[2:3], off
	global_load_dwordx4 v[86:89], v[2:3], off offset:32
	global_load_dwordx4 v[90:93], v[2:3], off offset:64
	global_load_dwordx4 v[94:97], v[2:3], off offset:96
	global_load_dwordx4 v[98:101], v[2:3], off offset:128
	global_load_dwordx4 v[102:105], v[2:3], off offset:160
	global_load_dwordx4 v[106:109], v[2:3], off offset:192
	global_load_dwordx4 v[110:113], v[2:3], off offset:224
	v_lshlrev_b32_e32 v184, 1, v180
	v_mov_b32_e32 v185, v1
	v_lshlrev_b64 v[2:3], s55, v[0:1]
	v_lshl_add_u64 v[190:191], s[8:9], 0, v[184:185]
	v_lshl_add_u64 v[2:3], v[2:3], 0, s[10:11]
	v_lshl_add_u64 v[188:189], s[8:9], 0, v[182:183]
	v_mad_u64_u32 v[4:5], s[8:9], v2, s83, v[190:191]
	v_mov_b32_e32 v0, v5
	v_mad_u64_u32 v[2:3], s[8:9], v3, s83, v[0:1]
	v_max_i32_e32 v0, 0xffffffe8, v10
	v_add_u32_e32 v0, 24, v0
	v_mov_b32_e32 v5, v2
	v_lshlrev_b64 v[2:3], s55, v[0:1]
	v_lshl_add_u64 v[2:3], v[2:3], 0, s[10:11]
	v_mad_u64_u32 v[6:7], s[8:9], v2, s83, v[190:191]
	v_mov_b32_e32 v0, v7
	v_mad_u64_u32 v[2:3], s[8:9], v3, s83, v[0:1]
	v_max_i32_e32 v0, 0xffffffec, v10
	v_add_u32_e32 v0, 20, v0
	v_mov_b32_e32 v7, v2
	v_lshlrev_b64 v[2:3], s55, v[0:1]
	v_lshl_add_u64 v[2:3], v[2:3], 0, s[10:11]
	global_load_dwordx4 v[142:145], v[4:5], off offset:768
	global_load_dwordx4 v[174:177], v[4:5], off offset:1536
	global_load_dwordx4 v[138:141], v[6:7], off offset:768
	global_load_dwordx4 v[170:173], v[6:7], off offset:1536
	v_mad_u64_u32 v[4:5], s[8:9], v2, s83, v[190:191]
	v_mov_b32_e32 v0, v5
	v_mad_u64_u32 v[2:3], s[8:9], v3, s83, v[0:1]
	v_max_i32_e32 v0, -16, v10
	v_add_u32_e32 v0, 16, v0
	v_mov_b32_e32 v5, v2
	v_lshlrev_b64 v[2:3], s55, v[0:1]
	v_lshl_add_u64 v[2:3], v[2:3], 0, s[10:11]
	v_mad_u64_u32 v[6:7], s[8:9], v2, s83, v[190:191]
	v_mov_b32_e32 v0, v7
	v_mad_u64_u32 v[2:3], s[8:9], v3, s83, v[0:1]
	v_max_i32_e32 v0, -12, v10
	v_add_u32_e32 v0, 12, v0
	v_mov_b32_e32 v7, v2
	v_lshlrev_b64 v[2:3], s55, v[0:1]
	v_lshl_add_u64 v[2:3], v[2:3], 0, s[10:11]
	global_load_dwordx4 v[134:137], v[4:5], off offset:768
	global_load_dwordx4 v[166:169], v[4:5], off offset:1536
	global_load_dwordx4 v[130:133], v[6:7], off offset:768
	global_load_dwordx4 v[162:165], v[6:7], off offset:1536
	v_mad_u64_u32 v[4:5], s[8:9], v2, s83, v[190:191]
	v_mov_b32_e32 v0, v5
	v_mad_u64_u32 v[2:3], s[8:9], v3, s83, v[0:1]
	v_max_i32_e32 v0, -8, v10
	v_add_u32_e32 v0, 8, v0
	v_mov_b32_e32 v5, v2
	v_lshlrev_b64 v[2:3], s55, v[0:1]
	v_lshl_add_u64 v[2:3], v[2:3], 0, s[10:11]
	v_mad_u64_u32 v[6:7], s[8:9], v2, s83, v[190:191]
	v_mov_b32_e32 v0, v7
	v_mad_u64_u32 v[2:3], s[8:9], v3, s83, v[0:1]
	v_max_i32_e32 v0, -4, v10
	v_add_u32_e32 v0, 4, v0
	v_mov_b32_e32 v7, v2
	v_lshlrev_b64 v[2:3], s55, v[0:1]
	v_lshl_add_u64 v[2:3], v[2:3], 0, s[10:11]
	global_load_dwordx4 v[126:129], v[4:5], off offset:768
	global_load_dwordx4 v[154:157], v[4:5], off offset:1536
	global_load_dwordx4 v[122:125], v[6:7], off offset:768
	global_load_dwordx4 v[158:161], v[6:7], off offset:1536
	v_mad_u64_u32 v[4:5], s[8:9], v2, s83, v[190:191]
	v_mov_b32_e32 v0, v5
	v_mad_u64_u32 v[2:3], s[8:9], v3, s83, v[0:1]
	v_max_i32_e32 v0, 0, v10
	v_mov_b32_e32 v5, v2
	v_lshlrev_b64 v[2:3], s55, v[0:1]
	v_lshl_add_u64 v[2:3], v[2:3], 0, s[10:11]
	v_mad_u64_u32 v[6:7], s[8:9], v2, s83, v[190:191]
	v_mov_b32_e32 v0, v7
	s_cmp_gt_i32 s51, -1
	v_cndmask_b32_e32 v9, 0, v201, vcc
	v_mad_u64_u32 v[2:3], s[8:9], v3, s83, v[0:1]
	v_or_b32_e32 v0, s51, v181
	s_cselect_b64 vcc, -1, 0
	v_mov_b32_e32 v7, v2
	v_cndmask_b32_e32 v2, 0, v0, vcc
	v_ashrrev_i32_e32 v3, 31, v2
	v_lshlrev_b64 v[2:3], s55, v[2:3]
	v_lshl_add_u64 v[2:3], v[2:3], 0, s[10:11]
	global_load_dwordx4 v[118:121], v[4:5], off offset:768
	global_load_dwordx4 v[146:149], v[4:5], off offset:1536
	global_load_dwordx4 v[114:117], v[6:7], off offset:768
	global_load_dwordx4 v[150:153], v[6:7], off offset:1536
	v_mad_u64_u32 v[4:5], s[8:9], v2, s83, v[188:189]
	v_mov_b32_e32 v0, v5
	v_mad_u64_u32 v[2:3], s[8:9], v3, s83, v[0:1]
	v_mov_b32_e32 v5, v2
	v_fmac_f32_e32 v9, -0.5, v8
	v_exp_f32_e32 v0, v9
	v_cvt_f32_u32_e32 v2, s19
	v_mov_b32_e32 v14, v1
	v_mov_b32_e32 v15, v1
	v_ldexp_f32 v0, v0, s16
	v_mul_f32_e32 v0, v0, v2
	v_mul_f32_e32 v185, 0x3fb8aa3b, v0
	v_mov_b32_e32 v0, v1
	v_mov_b32_e32 v2, v1
	v_mov_b32_e32 v3, v1
	v_mov_b32_e32 v4, v1
	v_mov_b32_e32 v5, v1
	v_mov_b32_e32 v6, v1
	v_mov_b32_e32 v7, v1
	v_mov_b32_e32 v8, v1
	v_mov_b32_e32 v9, v1
	v_mov_b32_e32 v10, v1
	v_mov_b32_e32 v11, v1
	v_mov_b32_e32 v12, v1
	v_mov_b32_e32 v13, v1
	v_mov_b64_e32 v[64:65], v[14:15]
	v_mov_b64_e32 v[48:49], v[14:15]
	v_mov_b64_e32 v[32:33], v[14:15]
	v_mov_b64_e32 v[62:63], v[12:13]
	v_mov_b64_e32 v[60:61], v[10:11]
	v_mov_b64_e32 v[58:59], v[8:9]
	v_mov_b64_e32 v[56:57], v[6:7]
	v_mov_b64_e32 v[54:55], v[4:5]
	v_mov_b64_e32 v[52:53], v[2:3]
	v_mov_b64_e32 v[50:51], v[0:1]
	v_mov_b64_e32 v[46:47], v[12:13]
	v_mov_b64_e32 v[44:45], v[10:11]
	v_mov_b64_e32 v[42:43], v[8:9]
	v_mov_b64_e32 v[40:41], v[6:7]
	v_mov_b64_e32 v[38:39], v[4:5]
	v_mov_b64_e32 v[36:37], v[2:3]
	v_mov_b64_e32 v[34:35], v[0:1]
	v_mov_b64_e32 v[30:31], v[12:13]
	v_mov_b64_e32 v[28:29], v[10:11]
	v_mov_b64_e32 v[26:27], v[8:9]
	v_mov_b64_e32 v[24:25], v[6:7]
	v_mov_b64_e32 v[22:23], v[4:5]
	v_mov_b64_e32 v[20:21], v[2:3]
	v_mov_b64_e32 v[18:19], v[0:1]
	v_mov_b64_e32 v[16:17], v[14:15]
	s_add_i32 s16, s17, -1
	v_subrev_u32_e32 v242, s18, v217
	v_mov_b32_e32 v243, 0
	v_mov_b32_e32 v244, 0xf149f2ca
	v_mov_b64_e32 v[14:15], v[12:13]
	v_mov_b64_e32 v[12:13], v[10:11]
	v_mov_b64_e32 v[10:11], v[8:9]
	v_mov_b64_e32 v[8:9], v[6:7]
	v_mov_b64_e32 v[6:7], v[4:5]
	v_mov_b64_e32 v[4:5], v[2:3]
	v_mov_b64_e32 v[2:3], v[0:1]
.LBB0_511:
	s_waitcnt vmcnt(0)
	ds_write_b128 v197, v[114:117]
	ds_write_b128 v197, v[118:121] offset:1088
	ds_write_b128 v197, v[122:125] offset:2176
	ds_write_b128 v197, v[126:129] offset:3264
	ds_write_b128 v197, v[130:133] offset:8704
	ds_write_b128 v197, v[134:137] offset:9792
	ds_write_b128 v197, v[138:141] offset:10880
	ds_write_b128 v197, v[142:145] offset:11968
	s_waitcnt lgkmcnt(0)
	ds_read_b128 v[114:117], v198
	ds_read_b128 v[118:121], v198 offset:32
	ds_read_b128 v[122:125], v198 offset:64
	ds_read_b128 v[126:129], v198 offset:96
	ds_read_b128 v[130:133], v198 offset:128
	ds_read_b128 v[134:137], v198 offset:160
	ds_read_b128 v[138:141], v198 offset:192
	ds_read_b128 v[142:145], v198 offset:224
	s_waitcnt lgkmcnt(0)
	v_mfma_f32_32x32x16_bf16 v[66:81], v[114:117], v[82:85], 0
	ds_write_b128 v218, v[150:153]
	ds_write_b128 v219, v[146:149]
	ds_write_b128 v220, v[158:161]
	ds_write_b128 v221, v[154:157]
	ds_write_b128 v222, v[162:165]
	ds_write_b128 v223, v[166:169]
	ds_write_b128 v224, v[170:173]
	ds_write_b128 v225, v[174:177]
	v_mfma_f32_32x32x16_bf16 v[66:81], v[118:121], v[86:89], v[66:81]
	v_mfma_f32_32x32x16_bf16 v[66:81], v[122:125], v[90:93], v[66:81]
	v_mfma_f32_32x32x16_bf16 v[66:81], v[126:129], v[94:97], v[66:81]
	v_mfma_f32_32x32x16_bf16 v[66:81], v[130:133], v[98:101], v[66:81]
	v_mfma_f32_32x32x16_bf16 v[66:81], v[134:137], v[102:105], v[66:81]
	v_mfma_f32_32x32x16_bf16 v[66:81], v[138:141], v[106:109], v[66:81]
	v_mfma_f32_32x32x16_bf16 v[66:81], v[142:145], v[110:113], v[66:81]
	s_cmp_eq_u32 s16, 3
	s_cbranch_scc1 .LBB0_513
	s_add_i32 s17, s51, 32
	s_cmp_gt_i32 s17, -1
	v_add_u32_e32 v0, s17, v181
	s_cselect_b64 vcc, -1, 0
	v_cndmask_b32_e32 v114, 0, v0, vcc
	v_ashrrev_i32_e32 v115, 31, v114
	v_lshlrev_b64 v[114:115], s55, v[114:115]
	v_lshl_add_u64 v[114:115], v[114:115], 0, s[10:11]
	v_mad_u64_u32 v[142:143], s[8:9], v114, s83, v[188:189]
	v_mov_b32_e32 v0, v143
	v_add_u32_e32 v174, s17, v204
	v_mad_u64_u32 v[114:115], s[8:9], v115, s83, v[0:1]
	v_max_i32_e32 v0, 0, v174
	v_lshlrev_b64 v[146:147], s55, v[0:1]
	v_lshl_add_u64 v[146:147], v[146:147], 0, s[10:11]
	v_mad_u64_u32 v[148:149], s[8:9], v146, s83, v[190:191]
	v_mov_b32_e32 v0, v149
	v_mad_u64_u32 v[146:147], s[8:9], v147, s83, v[0:1]
	v_max_i32_e32 v0, -4, v174
	v_add_u32_e32 v0, 4, v0
	v_mov_b32_e32 v149, v146
	v_lshlrev_b64 v[146:147], s55, v[0:1]
	v_lshl_add_u64 v[146:147], v[146:147], 0, s[10:11]
	v_mad_u64_u32 v[154:155], s[8:9], v146, s83, v[190:191]
	v_mov_b32_e32 v0, v155
	v_mad_u64_u32 v[146:147], s[8:9], v147, s83, v[0:1]
	v_max_i32_e32 v0, -8, v174
	v_mov_b32_e32 v143, v114
	v_mov_b32_e32 v155, v146
	v_add_u32_e32 v0, 8, v0
	s_nop 0
	s_nop 0
	global_load_dwordx4 v[114:117], v[148:149], off offset:768
	global_load_dwordx4 v[150:153], v[148:149], off offset:1536
	s_nop 0
	global_load_dwordx4 v[118:121], v[154:155], off offset:768
	global_load_dwordx4 v[146:149], v[154:155], off offset:1536
	v_lshlrev_b64 v[154:155], s55, v[0:1]
	v_lshl_add_u64 v[154:155], v[154:155], 0, s[10:11]
	v_mad_u64_u32 v[156:157], s[8:9], v154, s83, v[190:191]
	v_mov_b32_e32 v0, v157
	v_mad_u64_u32 v[154:155], s[8:9], v155, s83, v[0:1]
	v_max_i32_e32 v0, -12, v174
	v_add_u32_e32 v0, 12, v0
	v_mov_b32_e32 v157, v154
	v_lshlrev_b64 v[154:155], s55, v[0:1]
	v_lshl_add_u64 v[154:155], v[154:155], 0, s[10:11]
	v_mad_u64_u32 v[162:163], s[8:9], v154, s83, v[190:191]
	v_mov_b32_e32 v0, v163
	v_mad_u64_u32 v[154:155], s[8:9], v155, s83, v[0:1]
	v_max_i32_e32 v0, -16, v174
	v_mov_b32_e32 v163, v154
	v_add_u32_e32 v0, 16, v0
	global_load_dwordx4 v[122:125], v[156:157], off offset:768
	global_load_dwordx4 v[158:161], v[156:157], off offset:1536
	s_nop 0
	global_load_dwordx4 v[126:129], v[162:163], off offset:768
	global_load_dwordx4 v[154:157], v[162:163], off offset:1536
	v_lshlrev_b64 v[162:163], s55, v[0:1]
	v_lshl_add_u64 v[162:163], v[162:163], 0, s[10:11]
	v_mad_u64_u32 v[164:165], s[8:9], v162, s83, v[190:191]
	v_mov_b32_e32 v0, v165
	v_mad_u64_u32 v[162:163], s[8:9], v163, s83, v[0:1]
	v_max_i32_e32 v0, 0xffffffec, v174
	v_add_u32_e32 v0, 20, v0
	v_mov_b32_e32 v165, v162
	v_lshlrev_b64 v[162:163], s55, v[0:1]
	v_lshl_add_u64 v[162:163], v[162:163], 0, s[10:11]
	v_mad_u64_u32 v[166:167], s[8:9], v162, s83, v[190:191]
	v_mov_b32_e32 v0, v167
	v_mad_u64_u32 v[162:163], s[8:9], v163, s83, v[0:1]
	v_max_i32_e32 v0, 0xffffffe8, v174
	v_add_u32_e32 v0, 24, v0
	v_lshlrev_b64 v[170:171], s55, v[0:1]
	v_lshl_add_u64 v[170:171], v[170:171], 0, s[10:11]
	v_mad_u64_u32 v[172:173], s[8:9], v170, s83, v[190:191]
	v_mov_b32_e32 v0, v173
	v_mad_u64_u32 v[170:171], s[8:9], v171, s83, v[0:1]
	v_max_i32_e32 v0, 0xffffffe4, v174
	v_add_u32_e32 v0, 28, v0
	v_mov_b32_e32 v173, v170
	v_lshlrev_b64 v[170:171], s55, v[0:1]
	v_lshl_add_u64 v[170:171], v[170:171], 0, s[10:11]
	v_mad_u64_u32 v[174:175], s[8:9], v170, s83, v[190:191]
	v_mov_b32_e32 v0, v175
	v_mad_u64_u32 v[170:171], s[8:9], v171, s83, v[0:1]
	v_mov_b32_e32 v167, v162
	v_mov_b32_e32 v175, v170
	global_load_dwordx4 v[130:133], v[164:165], off offset:768
	global_load_dwordx4 v[162:165], v[164:165], off offset:1536
	s_nop 0
	global_load_dwordx4 v[134:137], v[166:167], off offset:768
	global_load_dwordx4 v[166:169], v[166:167], off offset:1536
	s_nop 0
	global_load_dwordx4 v[138:141], v[172:173], off offset:768
	global_load_dwordx4 v[170:173], v[172:173], off offset:1536
	s_nop 0
	global_load_dwordx4 v[142:145], v[174:175], off offset:768
	global_load_dwordx4 v[174:177], v[174:175], off offset:1536

.Ldilk_restore:
	v_readlane_b32 s4, v255, 2
	s_lshl_b32 s4, s4, 14
	v_lshl_add_u32 v0, v252, 3, s4
	v_add_u32_e32 v0, 0x3300, v0
	ds_read_b32 v197, v0
	ds_read_b32 v198, v0 offset:4
	s_waitcnt lgkmcnt(0)
